# phase-0 mod GEMV k-loop: 4 nt loads + LDS reads issued up front with counted vmcnt (was 4 serialized HBM round trips per iteration)
# speedup vs baseline: 1.0141x; 1.0141x over previous
.LBB0_1191:
	v_lshl_add_u64 v[52:53], v[18:19], 0, s[6:7]
	global_load_dwordx4 v[36:39], v[52:53], off nt
	v_lshl_add_u64 v[52:53], v[16:17], 0, s[6:7]
	global_load_dwordx4 v[40:43], v[52:53], off nt
	v_lshl_add_u64 v[52:53], v[14:15], 0, s[6:7]
	global_load_dwordx4 v[44:47], v[52:53], off nt
	v_lshl_add_u64 v[52:53], v[12:13], 0, s[6:7]
	global_load_dwordx4 v[48:51], v[52:53], off nt
	v_add_u32_e32 v34, 0x1000, v23
	v_add_u32_e32 v35, 0x2000, v23
	ds_read2_b32 v[28:29], v34 offset1:8
	ds_read2_b32 v[30:31], v35 offset1:8
	ds_read2_b32 v[32:33], v23 offset1:8
	ds_read2_b32 v[54:55], v23 offset0:16 offset1:24
	ds_read2_b32 v[56:57], v34 offset0:16 offset1:24
	ds_read2_b32 v[58:59], v35 offset0:16 offset1:24
	v_add_u32_e32 v22, 32, v22
	s_movk_i32 s12, 0x3df
	v_cmp_lt_i32_e32 vcc, s12, v22
	v_lshl_add_u64 v[18:19], v[18:19], 0, s[14:15]
	v_lshl_add_u64 v[16:17], v[16:17], 0, s[14:15]
	v_lshl_add_u64 v[14:15], v[14:15], 0, s[14:15]
	v_lshl_add_u64 v[12:13], v[12:13], 0, s[14:15]
	v_add_u32_e32 v23, 0x80, v23
	s_or_b64 s[8:9], vcc, s[8:9]
	s_waitcnt vmcnt(3) lgkmcnt(0)
	v_pk_fma_f32 v[4:5], v[32:33], v[36:37], v[4:5] op_sel_hi:[0,1,1]
	v_pk_fma_f32 v[8:9], v[36:37], v[28:29], v[8:9] op_sel_hi:[1,0,1]
	v_pk_fma_f32 v[0:1], v[36:37], v[30:31], v[0:1] op_sel_hi:[1,0,1]
	v_pk_fma_f32 v[6:7], v[32:33], v[38:39], v[6:7] op_sel_hi:[0,1,1]
	v_pk_fma_f32 v[10:11], v[38:39], v[28:29], v[10:11] op_sel_hi:[1,0,1]
	v_pk_fma_f32 v[2:3], v[38:39], v[30:31], v[2:3] op_sel_hi:[1,0,1]
	v_mov_b32_e32 v28, v33
	v_mov_b32_e32 v30, v29
	v_mov_b32_e32 v32, v31
	s_waitcnt vmcnt(2)
	v_pk_fma_f32 v[4:5], v[28:29], v[40:41], v[4:5] op_sel_hi:[0,1,1]
	v_pk_fma_f32 v[8:9], v[40:41], v[30:31], v[8:9] op_sel_hi:[1,0,1]
	v_pk_fma_f32 v[0:1], v[40:41], v[32:33], v[0:1] op_sel_hi:[1,0,1]
	v_pk_fma_f32 v[6:7], v[28:29], v[42:43], v[6:7] op_sel_hi:[0,1,1]
	v_pk_fma_f32 v[10:11], v[42:43], v[30:31], v[10:11] op_sel_hi:[1,0,1]
	v_pk_fma_f32 v[2:3], v[42:43], v[32:33], v[2:3] op_sel_hi:[1,0,1]
	s_waitcnt vmcnt(1)
	v_pk_fma_f32 v[4:5], v[54:55], v[44:45], v[4:5] op_sel_hi:[0,1,1]
	v_pk_fma_f32 v[8:9], v[44:45], v[56:57], v[8:9] op_sel_hi:[1,0,1]
	v_pk_fma_f32 v[0:1], v[44:45], v[58:59], v[0:1] op_sel_hi:[1,0,1]
	v_pk_fma_f32 v[6:7], v[54:55], v[46:47], v[6:7] op_sel_hi:[0,1,1]
	v_pk_fma_f32 v[10:11], v[46:47], v[56:57], v[10:11] op_sel_hi:[1,0,1]
	v_pk_fma_f32 v[2:3], v[46:47], v[58:59], v[2:3] op_sel_hi:[1,0,1]
	v_mov_b32_e32 v54, v55
	v_mov_b32_e32 v56, v57
	v_mov_b32_e32 v58, v59
	s_waitcnt vmcnt(0)
	v_pk_fma_f32 v[4:5], v[54:55], v[48:49], v[4:5] op_sel_hi:[0,1,1]
	v_pk_fma_f32 v[8:9], v[48:49], v[56:57], v[8:9] op_sel_hi:[1,0,1]
	v_pk_fma_f32 v[0:1], v[48:49], v[58:59], v[0:1] op_sel_hi:[1,0,1]
	v_pk_fma_f32 v[6:7], v[54:55], v[50:51], v[6:7] op_sel_hi:[0,1,1]
	v_pk_fma_f32 v[10:11], v[50:51], v[56:57], v[10:11] op_sel_hi:[1,0,1]
	v_pk_fma_f32 v[2:3], v[50:51], v[58:59], v[2:3] op_sel_hi:[1,0,1]
	s_andn2_b64 exec, exec, s[8:9]
	s_cbranch_execnz .LBB0_1191
	s_or_b64 exec, exec, s[8:9]
